# v31 + P2 V^T flush: three generic copy loops (1 dword per lane per store, ~25 VALU of 64-bit address math each) rewritten as straight-line code with 16-byte stores
# baseline (speedup 1.0000x reference)
.LBB0_753:
	v_mov_b32_e32 v2, v218
	s_movk_i32 s2, 0x1000
	s_nop 0
	v_cmp_gt_i32_e32 vcc, s2, v2
	s_and_saveexec_b64 s[10:11], vcc
	s_cbranch_execz .LBB0_761
	s_lshl_b64 s[14:15], s[18:19], 1
	v_readlane_b32 s16, v250, 41
	v_readlane_b32 s17, v250, 42
	s_add_u32 s14, s16, s14
	s_addc_u32 s15, s17, s15
	s_lshl_b32 s16, s59, 1
	s_add_u32 s14, s14, s16
	v_max_i32_e32 v0, 0xe00, v2
	s_addc_u32 s15, s15, 0
	v_sub_u32_e32 v0, v0, v2
	s_and_b64 s[16:17], s[12:13], exec
	v_add_u32_e32 v0, 0x1ff, v0
	s_cselect_b32 s68, 10, 8
	v_lshrrev_b32_e32 v0, 3, v218
	v_and_b32_e32 v3, 7, v218
	v_mul_u32_u24_e32 v2, 0x84, v0
	v_lshl_add_u32 v2, v3, 4, v2
	v_lshlrev_b32_e32 v4, s68, v0
	v_lshlrev_b32_e32 v4, 1, v4
	v_lshl_add_u32 v4, v3, 4, v4
	v_mov_b32_e32 v5, 0
	s_lshl_b32 s2, 0x80, s68
	v_lshl_add_u64 v[4:5], s[14:15], 0, v[4:5]
	ds_read_b32 v6, v2
	ds_read_b32 v7, v2 offset:4
	ds_read_b32 v8, v2 offset:8
	ds_read_b32 v9, v2 offset:12
	s_waitcnt lgkmcnt(0)
	global_store_dwordx4 v[4:5], v[6:9], off
	v_add_co_u32_e32 v4, vcc, s2, v4
	s_nop 1
	v_addc_co_u32_e32 v5, vcc, 0, v5, vcc
	ds_read_b32 v10, v2 offset:8448
	ds_read_b32 v11, v2 offset:8452
	ds_read_b32 v12, v2 offset:8456
	ds_read_b32 v13, v2 offset:8460
	s_waitcnt lgkmcnt(0)
	global_store_dwordx4 v[4:5], v[10:13], off
.LBB0_761:
	s_or_b64 exec, exec, s[10:11]
	v_mov_b32_e32 v2, v218
	s_movk_i32 s2, 0x2000
	s_nop 0
	v_cmp_gt_i32_e32 vcc, s2, v2
	s_and_saveexec_b64 s[10:11], vcc
	s_cbranch_execz .LBB0_769
	s_lshl_b64 s[8:9], s[8:9], 1
	v_readlane_b32 s14, v250, 35
	v_readlane_b32 s15, v250, 36
	s_add_u32 s8, s14, s8
	s_addc_u32 s9, s15, s9
	s_lshl_b32 s14, s59, 1
	s_add_u32 s8, s8, s14
	v_max_i32_e32 v0, 0x1e00, v2
	s_addc_u32 s9, s9, 0
	v_sub_u32_e32 v0, v0, v2
	s_and_b64 s[14:15], s[12:13], exec
	v_add_u32_e32 v0, 0x1ff, v0
	s_cselect_b32 s18, 10, 8
	v_lshrrev_b32_e32 v0, 3, v218
	v_and_b32_e32 v3, 7, v218
	v_mul_u32_u24_e32 v2, 0x84, v0
	v_lshl_add_u32 v2, v3, 4, v2
	v_lshlrev_b32_e32 v4, s18, v0
	v_lshlrev_b32_e32 v4, 1, v4
	v_lshl_add_u32 v4, v3, 4, v4
	v_mov_b32_e32 v5, 0
	s_lshl_b32 s2, 0x80, s18
	v_lshl_add_u64 v[4:5], s[8:9], 0, v[4:5]
	ds_read_b32 v6, v2 offset:16896
	ds_read_b32 v7, v2 offset:16900
	ds_read_b32 v8, v2 offset:16904
	ds_read_b32 v9, v2 offset:16908
	s_waitcnt lgkmcnt(0)
	global_store_dwordx4 v[4:5], v[6:9], off
	v_add_co_u32_e32 v4, vcc, s2, v4
	s_nop 1
	v_addc_co_u32_e32 v5, vcc, 0, v5, vcc
	ds_read_b32 v10, v2 offset:25344
	ds_read_b32 v11, v2 offset:25348
	ds_read_b32 v12, v2 offset:25352
	ds_read_b32 v13, v2 offset:25356
	s_waitcnt lgkmcnt(0)
	global_store_dwordx4 v[4:5], v[10:13], off
	v_add_co_u32_e32 v4, vcc, s2, v4
	s_nop 1
	v_addc_co_u32_e32 v5, vcc, 0, v5, vcc
	ds_read_b32 v6, v2 offset:33792
	ds_read_b32 v7, v2 offset:33796
	ds_read_b32 v8, v2 offset:33800
	ds_read_b32 v9, v2 offset:33804
	s_waitcnt lgkmcnt(0)
	global_store_dwordx4 v[4:5], v[6:9], off
	v_add_co_u32_e32 v4, vcc, s2, v4
	s_nop 1
	v_addc_co_u32_e32 v5, vcc, 0, v5, vcc
	ds_read_b32 v10, v2 offset:42240
	ds_read_b32 v11, v2 offset:42244
	ds_read_b32 v12, v2 offset:42248
	ds_read_b32 v13, v2 offset:42252
	s_waitcnt lgkmcnt(0)
	global_store_dwordx4 v[4:5], v[10:13], off
.LBB0_769:
	s_or_b64 exec, exec, s[10:11]
	v_mov_b32_e32 v2, v218
	s_movk_i32 s2, 0x2000
	s_nop 0
	v_cmp_gt_i32_e32 vcc, s2, v2
	s_and_saveexec_b64 s[8:9], vcc
	s_cbranch_execz .LBB0_642
	s_lshl_b64 s[0:1], s[0:1], 1
	v_readlane_b32 s10, v250, 45
	v_readlane_b32 s11, v250, 46
	s_add_u32 s0, s10, s0
	s_addc_u32 s1, s11, s1
	s_lshl_b32 s10, s59, 1
	s_add_u32 s0, s0, s10
	v_max_i32_e32 v0, 0x1e00, v2
	s_addc_u32 s1, s1, 0
	v_sub_u32_e32 v0, v0, v2
	s_and_b64 s[10:11], s[12:13], exec
	v_add_u32_e32 v0, 0x1ff, v0
	s_cselect_b32 s14, 10, 8
	v_lshrrev_b32_e32 v0, 3, v218
	v_and_b32_e32 v3, 7, v218
	v_mul_u32_u24_e32 v2, 0x84, v0
	v_lshl_add_u32 v2, v3, 4, v2
	v_add_u32_e32 v2, 0xc600, v2
	v_lshlrev_b32_e32 v4, s14, v0
	v_lshlrev_b32_e32 v4, 1, v4
	v_lshl_add_u32 v4, v3, 4, v4
	v_mov_b32_e32 v5, 0
	s_lshl_b32 s2, 0x80, s14
	v_lshl_add_u64 v[4:5], s[0:1], 0, v[4:5]
	ds_read_b32 v6, v2
	ds_read_b32 v7, v2 offset:4
	ds_read_b32 v8, v2 offset:8
	ds_read_b32 v9, v2 offset:12
	s_waitcnt lgkmcnt(0)
	global_store_dwordx4 v[4:5], v[6:9], off
	v_add_co_u32_e32 v4, vcc, s2, v4
	s_nop 1
	v_addc_co_u32_e32 v5, vcc, 0, v5, vcc
	ds_read_b32 v10, v2 offset:8448
	ds_read_b32 v11, v2 offset:8452
	ds_read_b32 v12, v2 offset:8456
	ds_read_b32 v13, v2 offset:8460
	s_waitcnt lgkmcnt(0)
	global_store_dwordx4 v[4:5], v[10:13], off
	v_add_co_u32_e32 v4, vcc, s2, v4
	s_nop 1
	v_addc_co_u32_e32 v5, vcc, 0, v5, vcc
	ds_read_b32 v6, v2 offset:16896
	ds_read_b32 v7, v2 offset:16900
	ds_read_b32 v8, v2 offset:16904
	ds_read_b32 v9, v2 offset:16908
	s_waitcnt lgkmcnt(0)
	global_store_dwordx4 v[4:5], v[6:9], off
	v_add_co_u32_e32 v4, vcc, s2, v4
	s_nop 1
	v_addc_co_u32_e32 v5, vcc, 0, v5, vcc
	ds_read_b32 v10, v2 offset:25344
	ds_read_b32 v11, v2 offset:25348
	ds_read_b32 v12, v2 offset:25352
	ds_read_b32 v13, v2 offset:25356
	s_waitcnt lgkmcnt(0)
	global_store_dwordx4 v[4:5], v[10:13], off
	s_branch .LBB0_642
